# tile order: panel groups (6,6,5) for gemm1/gemmG/gemm4 and (8,9) for the N=1024 GEMMs (gemmU, gres16, gres44)
# speedup vs baseline: 1.0518x; 1.0096x over previous
.LBB0_679:
	s_cmp_ge_u32 s3, 64
	s_cbranch_scc1 .Lto_g1_b0
	s_sub_u32 s99, s3, 0
	s_lshr_b32 s98, s99, 3
	s_and_b32 s99, s99, 7
	s_branch .Lto_j_b0
.Lto_g1_b0:
	s_sub_u32 s99, s3, 64
	s_mul_hi_u32 s98, s99, 0x38e38e39
	s_lshr_b32 s98, s98, 1
	s_mul_i32 s100, s98, 9
	s_sub_u32 s99, s99, s100
	s_add_u32 s99, s99, 8
.Lto_j_b0:
	s_mul_i32 s98, s98, 17
	s_add_u32 s98, s98, s99
	s_lshl_b32 s99, s98, 3
	s_or_b32 s99, s99, s86
	s_mul_hi_i32 s0, s98, 0x78787879
	s_lshr_b32 s12, s0, 31
	s_ashr_i32 s0, s0, 3
	s_add_i32 s0, s0, s12
	s_mul_i32 s12, s0, 0xffffffef
	s_add_i32 s12, s12, s98
	s_lshl_b32 s12, s12, 3
	s_or_b32 s12, s12, s86
	v_lshl_add_u32 v132, s12, 7, v177
	s_lshl_b32 s34, s0, 7
	v_ashrrev_i32_e32 v133, 31, v132
	v_or_b32_e32 v134, s34, v176
	v_lshlrev_b64 v[2:3], 13, v[132:133]
	v_lshl_add_u64 v[2:3], s[42:43], 0, v[2:3]
	v_ashrrev_i32_e32 v135, 31, v134
	v_mov_b32_e32 v0, v174
	v_lshl_add_u64 v[136:137], v[134:135], 1, v[2:3]
	s_ashr_i32 s13, s12, 31
	v_bfe_u32 v3, v0, 1, 3
	s_waitcnt vmcnt(5)
	v_lshrrev_b32_e32 v4, 4, v0
	v_bfe_u32 v5, v0, 4, 2
	v_lshlrev_b32_e32 v6, 7, v0
	v_and_b32_e32 v7, 0x780, v6
	v_bitop3_b32 v4, v4, v3, 3 bitop3:0x6c
	v_bitop3_b32 v3, v5, v3, 4 bitop3:0x36
	v_lshl_or_b32 v179, v3, 4, v7
	v_lshlrev_b32_e32 v3, 6, v0
	v_lshlrev_b32_e32 v2, 8, v0
	v_and_b32_e32 v8, 0xffffe000, v3
	v_lshlrev_b32_e32 v3, 4, v0
	s_lshl_b64 s[12:13], s[12:13], 18
	v_and_b32_e32 v2, 0xfffff800, v2
	v_xor_b32_e32 v0, v3, v0
	s_movk_i32 s91, 0x70
	v_add_u32_e32 v180, 0, v3
	s_add_u32 s12, s40, s12
	v_and_or_b32 v0, v0, s91, v2
	v_readfirstlane_b32 s91, v180
	v_add_u32_e32 v181, 0x1000, v180
	s_addc_u32 s13, s41, s13
	s_mov_b32 m0, s91
	v_readfirstlane_b32 s91, v181
	v_add_u32_e32 v182, 0x2000, v180
	global_load_lds_dwordx4 v0, s[12:13]
	v_add_u32_e32 v2, 0x10000, v0
	s_mov_b32 m0, s91
	v_readfirstlane_b32 s91, v182
	v_add_u32_e32 v183, 0x3000, v180
	s_ashr_i32 s35, s34, 31
	v_lshl_or_b32 v178, v4, 4, v7
	global_load_lds_dwordx4 v2, s[12:13]
	v_add_u32_e32 v4, 0x20000, v0
	s_mov_b32 m0, s91
	v_readfirstlane_b32 s91, v183
	s_lshl_b64 s[34:35], s[34:35], 11
	v_and_b32_e32 v9, 0x2000, v6
	global_load_lds_dwordx4 v4, s[12:13]
	v_add_u32_e32 v6, 0x30000, v0
	s_mov_b32 m0, s91
	v_add_u32_e32 v184, 0x4000, v180
	s_add_u32 s84, s88, s34
	global_load_lds_dwordx4 v6, s[12:13]
	v_readfirstlane_b32 s12, v184
	v_add_u32_e32 v185, 0x5000, v180
	s_addc_u32 s85, s89, s35
	s_mov_b32 m0, s12
	v_readfirstlane_b32 s12, v185
	v_add_u32_e32 v186, 0x6000, v180
	global_load_lds_dwordx4 v0, s[84:85]
	s_mov_b32 m0, s12
	v_readfirstlane_b32 s12, v186
	v_add_u32_e32 v187, 0x7000, v180
	global_load_lds_dwordx4 v2, s[84:85]
	s_mov_b32 m0, s12
	v_readfirstlane_b32 s12, v187
	global_load_lds_dwordx4 v4, s[84:85]
	s_mov_b32 m0, s12
	s_mov_b64 s[12:13], 0x20000
	global_load_lds_dwordx4 v6, s[84:85]
	v_lshl_add_u64 v[138:139], v[136:137], 0, s[12:13]
	s_mov_b64 s[12:13], 0x40000
	v_lshl_add_u64 v[140:141], v[136:137], 0, s[12:13]
	s_mov_b64 s[12:13], 0x60000
	s_mulk_i32 s0, 0x88
	v_lshl_add_u64 v[142:143], v[136:137], 0, s[12:13]
	s_sub_i32 s12, s99, s0
	s_ashr_i32 s13, s12, 31
	s_lshl_b64 s[12:13], s[12:13], 18
	s_add_u32 s12, s40, s12
	v_mov_b32_e32 v3, v1
	v_mov_b32_e32 v5, v1
	v_mov_b32_e32 v7, v1
	s_addc_u32 s13, s41, s13
	v_lshl_add_u64 v[144:145], s[12:13], 0, v[0:1]
	v_lshl_add_u64 v[146:147], s[12:13], 0, v[2:3]
	v_lshl_add_u64 v[148:149], s[12:13], 0, v[4:5]
	v_lshl_add_u64 v[150:151], s[12:13], 0, v[6:7]
	s_add_u32 s12, s36, s34
	s_addc_u32 s13, s37, s35
	v_lshl_add_u64 v[154:155], s[12:13], 0, v[2:3]
	v_mov_b32_e32 v2, v1
	v_add_u32_e32 v188, 0, v8
	v_add_u32_e32 v189, 0, v9
	v_lshl_add_u64 v[152:153], s[12:13], 0, v[0:1]
	v_lshl_add_u64 v[156:157], s[12:13], 0, v[4:5]
	v_lshl_add_u64 v[158:159], s[12:13], 0, v[6:7]
	v_mov_b32_e32 v0, v1
	v_mov_b64_e32 v[6:7], v[2:3]
	v_mov_b64_e32 v[10:11], v[2:3]
	v_mov_b64_e32 v[14:15], v[2:3]
	v_mov_b64_e32 v[18:19], v[2:3]
	v_mov_b64_e32 v[22:23], v[2:3]
	v_mov_b64_e32 v[26:27], v[2:3]
	v_mov_b64_e32 v[30:31], v[2:3]
	v_mov_b64_e32 v[34:35], v[2:3]
	v_mov_b64_e32 v[38:39], v[2:3]
	v_mov_b64_e32 v[42:43], v[2:3]
	v_mov_b64_e32 v[46:47], v[2:3]
	v_mov_b64_e32 v[50:51], v[2:3]
	s_waitcnt vmcnt(0)
	v_mov_b64_e32 v[54:55], v[2:3]
	v_mov_b64_e32 v[58:59], v[2:3]
	v_mov_b64_e32 v[62:63], v[2:3]
	v_mov_b64_e32 v[66:67], v[2:3]
	s_mov_b64 s[12:13], 0
	s_mov_b32 s91, s1
	v_mov_b64_e32 v[4:5], v[0:1]
	v_mov_b64_e32 v[8:9], v[0:1]
	v_mov_b64_e32 v[12:13], v[0:1]
	v_mov_b64_e32 v[16:17], v[0:1]
	v_mov_b64_e32 v[20:21], v[0:1]
	v_mov_b64_e32 v[24:25], v[0:1]
	v_mov_b64_e32 v[28:29], v[0:1]
	v_mov_b64_e32 v[32:33], v[0:1]
	v_mov_b64_e32 v[36:37], v[0:1]
	v_mov_b64_e32 v[40:41], v[0:1]
	v_mov_b64_e32 v[44:45], v[0:1]
	v_mov_b64_e32 v[48:49], v[0:1]
	v_mov_b64_e32 v[52:53], v[0:1]
	v_mov_b64_e32 v[56:57], v[0:1]
	v_mov_b64_e32 v[60:61], v[0:1]
	v_mov_b64_e32 v[64:65], v[0:1]
	s_mov_b32 s92, s1
	v_mov_b32_e32 v68, 0
	v_mov_b32_e32 v69, v1
	v_mov_b32_e32 v70, v1
	v_mov_b32_e32 v71, v1
	v_mov_b32_e32 v72, 0
	v_mov_b32_e32 v73, v1
	v_mov_b32_e32 v74, v1
	v_mov_b32_e32 v75, v1
	v_mov_b32_e32 v76, 0
	v_mov_b32_e32 v77, v1
	v_mov_b32_e32 v78, v1
	v_mov_b32_e32 v79, v1
	v_mov_b32_e32 v80, 0
	v_mov_b32_e32 v81, v1
	v_mov_b32_e32 v82, v1
	v_mov_b32_e32 v83, v1
	v_mov_b32_e32 v84, 0
	v_mov_b32_e32 v85, v1
	v_mov_b32_e32 v86, v1
	v_mov_b32_e32 v87, v1
	v_mov_b32_e32 v88, 0
	v_mov_b32_e32 v89, v1
	v_mov_b32_e32 v90, v1
	v_mov_b32_e32 v91, v1
	v_mov_b32_e32 v92, 0
	v_mov_b32_e32 v93, v1
	v_mov_b32_e32 v94, v1
	v_mov_b32_e32 v95, v1
	v_mov_b32_e32 v96, 0
	v_mov_b32_e32 v97, v1
	v_mov_b32_e32 v98, v1
	v_mov_b32_e32 v99, v1
	v_mov_b32_e32 v100, 0
	v_mov_b32_e32 v101, v1
	v_mov_b32_e32 v102, v1
	v_mov_b32_e32 v103, v1
	v_mov_b32_e32 v104, 0
	v_mov_b32_e32 v105, v1
	v_mov_b32_e32 v106, v1
	v_mov_b32_e32 v107, v1
	v_mov_b32_e32 v108, 0
	v_mov_b32_e32 v109, v1
	v_mov_b32_e32 v110, v1
	v_mov_b32_e32 v111, v1
	v_mov_b32_e32 v112, 0
	v_mov_b32_e32 v113, v1
	v_mov_b32_e32 v114, v1
	v_mov_b32_e32 v115, v1
	v_mov_b32_e32 v116, 0
	v_mov_b32_e32 v117, v1
	v_mov_b32_e32 v118, v1
	v_mov_b32_e32 v119, v1
	v_mov_b32_e32 v120, 0
	v_mov_b32_e32 v121, v1
	v_mov_b32_e32 v122, v1
	v_mov_b32_e32 v123, v1
	v_mov_b32_e32 v124, 0
	v_mov_b32_e32 v125, v1
	v_mov_b32_e32 v126, v1
	v_mov_b32_e32 v127, v1
	v_mov_b32_e32 v128, 0
	v_mov_b32_e32 v129, v1
	v_mov_b32_e32 v130, v1
	v_mov_b32_e32 v131, v1
	s_branch .LBB0_681

.Lto_j_b1:
	s_mul_i32 s98, s98, 17
	s_add_u32 s98, s98, s99
	s_lshl_b32 s99, s98, 3
	s_or_b32 s99, s99, s90
	s_mul_hi_i32 s10, s98, 0x78787879
	s_lshr_b32 s11, s10, 31
	s_ashr_i32 s10, s10, 3
	s_add_i32 s10, s10, s11
	s_mul_i32 s11, s10, 0xffffffef
	s_add_i32 s11, s11, s98
	s_lshl_b32 s11, s11, 3
	s_or_b32 s12, s11, s90
	v_mov_b32_e32 v0, v174
	s_ashr_i32 s13, s12, 31
	s_lshl_b64 s[34:35], s[12:13], 18
	v_bfe_u32 v2, v0, 1, 3
	v_lshrrev_b32_e32 v3, 4, v0
	s_waitcnt vmcnt(5)
	v_bfe_u32 v4, v0, 4, 2
	v_lshlrev_b32_e32 v5, 7, v0
	v_and_b32_e32 v6, 0x780, v5
	v_bitop3_b32 v3, v3, v2, 3 bitop3:0x6c
	v_bitop3_b32 v2, v4, v2, 4 bitop3:0x36
	s_add_u32 s34, s38, s34
	v_lshl_or_b32 v7, v3, 4, v6
	v_lshl_or_b32 v6, v2, 4, v6
	v_lshlrev_b32_e32 v2, 6, v0
	s_addc_u32 s35, s39, s35
	s_ashr_i32 s11, s10, 31
	v_lshlrev_b32_e32 v1, 8, v0
	v_and_b32_e32 v8, 0xffffe000, v2
	v_lshlrev_b32_e32 v2, 4, v0
	s_lshl_b64 s[84:85], s[10:11], 18
	v_and_b32_e32 v1, 0xfffff800, v1
	v_xor_b32_e32 v0, v2, v0
	s_movk_i32 s11, 0x70
	v_add_u32_e32 v100, 0, v2
	v_and_or_b32 v64, v0, s11, v1
	v_readfirstlane_b32 s11, v100
	v_add_u32_e32 v101, 0x1000, v100
	s_mov_b32 m0, s11
	v_readfirstlane_b32 s11, v101
	v_add_u32_e32 v102, 0x2000, v100
	global_load_lds_dwordx4 v64, s[34:35]
	v_add_u32_e32 v0, 0x10000, v64
	s_mov_b32 m0, s11
	v_readfirstlane_b32 s11, v102
	v_add_u32_e32 v103, 0x3000, v100
	global_load_lds_dwordx4 v0, s[34:35]
	v_add_u32_e32 v2, 0x20000, v64
	s_mov_b32 m0, s11
	v_readfirstlane_b32 s11, v103
	v_add_u32_e32 v104, 0x4000, v100
	s_add_u32 s88, s70, s84
	global_load_lds_dwordx4 v2, s[34:35]
	v_add_u32_e32 v4, 0x30000, v64
	s_mov_b32 m0, s11
	v_readfirstlane_b32 s11, v104
	v_add_u32_e32 v105, 0x5000, v100
	s_addc_u32 s89, s71, s85
	global_load_lds_dwordx4 v4, s[34:35]
	s_mov_b32 m0, s11
	v_readfirstlane_b32 s11, v105
	v_add_u32_e32 v106, 0x6000, v100
	global_load_lds_dwordx4 v64, s[88:89]
	s_mov_b32 m0, s11
	v_readfirstlane_b32 s11, v106
	v_add_u32_e32 v107, 0x7000, v100
	global_load_lds_dwordx4 v0, s[88:89]
	s_mov_b32 m0, s11
	v_readfirstlane_b32 s11, v107
	global_load_lds_dwordx4 v2, s[88:89]
	s_mov_b32 m0, s11
	s_mul_i32 s11, s10, 0x88
	global_load_lds_dwordx4 v4, s[88:89]
	s_sub_i32 s34, s99, s11
	s_ashr_i32 s35, s34, 31
	s_lshl_b64 s[34:35], s[34:35], 18
	s_add_u32 s34, s38, s34
	v_and_b32_e32 v9, 0x2000, v5
	v_mov_b32_e32 v1, v65
	v_mov_b32_e32 v3, v65
	v_mov_b32_e32 v5, v65
	s_addc_u32 s35, s39, s35
	v_lshl_add_u64 v[66:67], s[34:35], 0, v[64:65]
	v_lshl_add_u64 v[68:69], s[34:35], 0, v[0:1]
	v_lshl_add_u64 v[70:71], s[34:35], 0, v[2:3]
	v_lshl_add_u64 v[72:73], s[34:35], 0, v[4:5]
	s_add_u32 s34, s36, s84
	v_add_u32_e32 v8, 0, v8
	v_add_u32_e32 v9, 0, v9
	s_addc_u32 s35, s37, s85
	v_lshl_add_u64 v[74:75], s[34:35], 0, v[64:65]
	v_lshl_add_u64 v[76:77], s[34:35], 0, v[0:1]
	v_lshl_add_u64 v[78:79], s[34:35], 0, v[2:3]
	v_lshl_add_u64 v[80:81], s[34:35], 0, v[4:5]
	s_mov_b64 s[84:85], 0
	v_add_u32_e32 v64, 0x8000, v100
	v_add_u32_e32 v108, 0x9000, v100
	v_add_u32_e32 v109, 0xa000, v100
	v_add_u32_e32 v110, 0xb000, v100
	v_add_u32_e32 v111, 0xc000, v100
	v_add_u32_e32 v112, 0xd000, v100
	v_add_u32_e32 v113, 0xe000, v100
	v_add_u32_e32 v114, 0xf000, v100
	v_add_u32_e32 v115, v8, v7
	v_add_u32_e32 v116, v9, v7
	v_add_u32_e32 v117, v8, v6
	v_add_u32_e32 v118, v9, v6
	s_mov_b32 s11, 0
	v_mov_b32_e32 v0, 0
	v_mov_b32_e32 v2, v65
	v_mov_b32_e32 v4, 0
	v_mov_b32_e32 v6, v65
	v_mov_b32_e32 v7, v65
	v_mov_b32_e32 v8, 0
	v_mov_b32_e32 v9, v65
	v_mov_b32_e32 v10, v65
	v_mov_b32_e32 v11, v65
	v_mov_b32_e32 v12, 0
	v_mov_b32_e32 v13, v65
	v_mov_b32_e32 v14, v65
	v_mov_b32_e32 v15, v65
	v_mov_b32_e32 v16, 0
	v_mov_b32_e32 v17, v65
	v_mov_b32_e32 v18, v65
	v_mov_b32_e32 v19, v65
	v_mov_b32_e32 v20, 0
	v_mov_b32_e32 v21, v65
	v_mov_b32_e32 v22, v65
	v_mov_b32_e32 v23, v65
	v_mov_b32_e32 v24, 0
	v_mov_b32_e32 v25, v65
	v_mov_b32_e32 v26, v65
	v_mov_b32_e32 v27, v65
	v_mov_b32_e32 v28, 0
	v_mov_b32_e32 v29, v65
	v_mov_b32_e32 v30, v65
	v_mov_b32_e32 v31, v65
	v_mov_b32_e32 v32, 0
	v_mov_b32_e32 v33, v65
	v_mov_b32_e32 v34, v65
	v_mov_b32_e32 v35, v65
	v_mov_b32_e32 v36, 0
	v_mov_b32_e32 v37, v65
	v_mov_b32_e32 v38, v65
	v_mov_b32_e32 v39, v65
	v_mov_b32_e32 v40, 0
	v_mov_b32_e32 v41, v65
	v_mov_b32_e32 v42, v65
	v_mov_b32_e32 v43, v65
	v_mov_b32_e32 v44, 0
	v_mov_b32_e32 v45, v65
	v_mov_b32_e32 v46, v65
	v_mov_b32_e32 v47, v65
	v_mov_b32_e32 v48, 0
	v_mov_b32_e32 v49, v65
	v_mov_b32_e32 v50, v65
	v_mov_b32_e32 v51, v65
	v_mov_b32_e32 v52, 0
	v_mov_b32_e32 v53, v65
	s_waitcnt vmcnt(0)
	v_mov_b32_e32 v54, v65
	v_mov_b32_e32 v55, v65
	v_mov_b32_e32 v56, 0
	v_mov_b32_e32 v57, v65
	v_mov_b32_e32 v58, v65
	v_mov_b32_e32 v59, v65
	v_mov_b32_e32 v60, 0
	v_mov_b32_e32 v61, v65
	v_mov_b32_e32 v62, v65
	v_mov_b32_e32 v63, v65
	s_branch .LBB0_752

.Lto_j_b2:
	s_mul_i32 s98, s98, 17
	s_add_u32 s98, s98, s99
	s_lshl_b32 s99, s98, 3
	s_or_b32 s99, s99, s84
	s_mul_hi_i32 s10, s98, 0x78787879
	s_lshr_b32 s11, s10, 31
	s_ashr_i32 s91, s10, 3
	s_add_i32 s91, s91, s11
	v_mov_b32_e32 v0, v174
	s_mul_i32 s10, s91, 0xffffffef
	s_add_i32 s10, s10, s98
	v_bfe_u32 v2, v0, 1, 3
	v_lshrrev_b32_e32 v3, 4, v0
	s_waitcnt vmcnt(5)
	v_bfe_u32 v4, v0, 4, 2
	v_lshlrev_b32_e32 v5, 7, v0
	v_and_b32_e32 v6, 0x780, v5
	v_bitop3_b32 v3, v3, v2, 3 bitop3:0x6c
	v_bitop3_b32 v2, v4, v2, 4 bitop3:0x36
	s_lshl_b32 s10, s10, 3
	v_lshl_or_b32 v7, v3, 4, v6
	v_lshl_or_b32 v6, v2, 4, v6
	v_lshlrev_b32_e32 v2, 6, v0
	s_or_b32 s92, s10, s84
	v_lshrrev_b32_e32 v1, 3, v0
	v_and_b32_e32 v8, 0xffffe000, v2
	s_movk_i32 s93, 0x1600
	v_lshlrev_b32_e32 v2, 4, v0
	s_mul_i32 s10, s92, 0xb0000
	v_mul_lo_u32 v1, v1, s93
	v_xor_b32_e32 v0, v2, v0
	s_movk_i32 s93, 0x70
	v_add_u32_e32 v100, 0, v2
	s_mul_hi_i32 s11, s92, 0xb0000
	s_add_u32 s10, s42, s10
	v_and_or_b32 v64, v0, s93, v1
	v_readfirstlane_b32 s93, v100
	v_add_u32_e32 v101, 0x1000, v100
	s_addc_u32 s11, s43, s11
	s_mov_b32 m0, s93
	v_readfirstlane_b32 s93, v101
	v_add_u32_e32 v102, 0x2000, v100
	global_load_lds_dwordx4 v64, s[10:11]
	v_add_u32_e32 v0, 0x2c000, v64
	s_mov_b32 m0, s93
	v_readfirstlane_b32 s93, v102
	v_add_u32_e32 v103, 0x3000, v100
	global_load_lds_dwordx4 v0, s[10:11]
	v_add_u32_e32 v2, 0x58000, v64
	s_mov_b32 m0, s93
	v_readfirstlane_b32 s93, v103
	s_mul_i32 s35, s91, 0xb0000
	global_load_lds_dwordx4 v2, s[10:11]
	v_add_u32_e32 v4, 0x84000, v64
	s_mov_b32 m0, s93
	v_add_u32_e32 v104, 0x4000, v100
	s_mul_hi_i32 s34, s91, 0xb0000
	s_add_u32 s12, s88, s35
	global_load_lds_dwordx4 v4, s[10:11]
	v_readfirstlane_b32 s10, v104
	v_add_u32_e32 v105, 0x5000, v100
	s_addc_u32 s13, s89, s34
	s_mov_b32 m0, s10
	v_readfirstlane_b32 s10, v105
	v_add_u32_e32 v106, 0x6000, v100
	global_load_lds_dwordx4 v64, s[12:13]
	s_mov_b32 m0, s10
	v_readfirstlane_b32 s10, v106
	v_add_u32_e32 v107, 0x7000, v100
	global_load_lds_dwordx4 v0, s[12:13]
	s_mov_b32 m0, s10
	v_readfirstlane_b32 s10, v107
	global_load_lds_dwordx4 v2, s[12:13]
	s_mov_b32 m0, s10
	s_mul_i32 s10, s91, 0x88
	global_load_lds_dwordx4 v4, s[12:13]
	s_sub_i32 s10, s99, s10
	s_mul_hi_i32 s11, s10, 0xb0000
	s_mul_i32 s10, s10, 0xb0000
	s_add_u32 s10, s42, s10
	v_and_b32_e32 v9, 0x2000, v5
	v_mov_b32_e32 v1, v65
	v_mov_b32_e32 v3, v65
	v_mov_b32_e32 v5, v65
	s_addc_u32 s11, s43, s11
	v_lshl_add_u64 v[66:67], s[10:11], 0, v[64:65]
	v_lshl_add_u64 v[68:69], s[10:11], 0, v[0:1]
	v_lshl_add_u64 v[70:71], s[10:11], 0, v[2:3]
	v_lshl_add_u64 v[72:73], s[10:11], 0, v[4:5]
	s_add_u32 s10, s36, s35
	v_add_u32_e32 v8, 0, v8
	v_add_u32_e32 v9, 0, v9
	s_addc_u32 s11, s37, s34
	v_lshl_add_u64 v[74:75], s[10:11], 0, v[64:65]
	v_lshl_add_u64 v[76:77], s[10:11], 0, v[0:1]
	v_lshl_add_u64 v[78:79], s[10:11], 0, v[2:3]
	v_lshl_add_u64 v[80:81], s[10:11], 0, v[4:5]
	s_mov_b64 s[10:11], 0
	v_add_u32_e32 v64, 0x8000, v100
	v_add_u32_e32 v108, 0x9000, v100
	v_add_u32_e32 v109, 0xa000, v100
	v_add_u32_e32 v110, 0xb000, v100
	v_add_u32_e32 v111, 0xc000, v100
	v_add_u32_e32 v112, 0xd000, v100
	v_add_u32_e32 v113, 0xe000, v100
	v_add_u32_e32 v114, 0xf000, v100
	v_add_u32_e32 v115, v8, v7
	v_add_u32_e32 v116, v9, v7
	v_add_u32_e32 v117, v8, v6
	v_add_u32_e32 v118, v9, v6
	s_mov_b32 s93, 0
	v_mov_b32_e32 v0, 0
	v_mov_b32_e32 v2, v65
	v_mov_b32_e32 v4, 0
	v_mov_b32_e32 v6, v65
	v_mov_b32_e32 v7, v65
	v_mov_b32_e32 v8, 0
	v_mov_b32_e32 v9, v65
	v_mov_b32_e32 v10, v65
	v_mov_b32_e32 v11, v65
	v_mov_b32_e32 v12, 0
	v_mov_b32_e32 v13, v65
	v_mov_b32_e32 v14, v65
	v_mov_b32_e32 v15, v65
	v_mov_b32_e32 v16, 0
	v_mov_b32_e32 v17, v65
	v_mov_b32_e32 v18, v65
	v_mov_b32_e32 v19, v65
	v_mov_b32_e32 v20, 0
	v_mov_b32_e32 v21, v65
	v_mov_b32_e32 v22, v65
	v_mov_b32_e32 v23, v65
	v_mov_b32_e32 v24, 0
	v_mov_b32_e32 v25, v65
	v_mov_b32_e32 v26, v65
	v_mov_b32_e32 v27, v65
	v_mov_b32_e32 v28, 0
	v_mov_b32_e32 v29, v65
	v_mov_b32_e32 v30, v65
	v_mov_b32_e32 v31, v65
	v_mov_b32_e32 v32, 0
	v_mov_b32_e32 v33, v65
	v_mov_b32_e32 v34, v65
	v_mov_b32_e32 v35, v65
	v_mov_b32_e32 v36, 0
	v_mov_b32_e32 v37, v65
	v_mov_b32_e32 v38, v65
	v_mov_b32_e32 v39, v65
	v_mov_b32_e32 v40, 0
	v_mov_b32_e32 v41, v65
	v_mov_b32_e32 v42, v65
	v_mov_b32_e32 v43, v65
	v_mov_b32_e32 v44, 0
	v_mov_b32_e32 v45, v65
	v_mov_b32_e32 v46, v65
	v_mov_b32_e32 v47, v65
	v_mov_b32_e32 v48, 0
	v_mov_b32_e32 v49, v65
	v_mov_b32_e32 v50, v65
	v_mov_b32_e32 v51, v65
	v_mov_b32_e32 v52, 0
	v_mov_b32_e32 v53, v65
	s_waitcnt vmcnt(0)
	v_mov_b32_e32 v54, v65
	v_mov_b32_e32 v55, v65
	v_mov_b32_e32 v56, 0
	v_mov_b32_e32 v57, v65
	v_mov_b32_e32 v58, v65
	v_mov_b32_e32 v59, v65
	v_mov_b32_e32 v60, 0
	v_mov_b32_e32 v61, v65
	v_mov_b32_e32 v62, v65
	v_mov_b32_e32 v63, v65
	s_branch .LBB0_953

.Lto_j_b3:
	s_mul_i32 s98, s98, 17
	s_add_u32 s98, s98, s99
	s_lshl_b32 s99, s98, 3
	s_or_b32 s99, s99, s26
	s_mul_hi_i32 s0, s98, 0x78787879
	s_lshr_b32 s20, s0, 31
	s_ashr_i32 s0, s0, 3
	s_add_i32 s0, s0, s20
	s_mul_i32 s20, s0, 0xffffffef
	s_add_i32 s20, s20, s98
	s_lshl_b32 s20, s20, 3
	s_or_b32 s20, s20, s26
	v_lshl_add_u32 v132, s20, 7, v177
	s_lshl_b32 s24, s0, 7
	v_ashrrev_i32_e32 v133, 31, v132
	v_or_b32_e32 v134, s24, v176
	v_lshlrev_b64 v[2:3], 13, v[132:133]
	v_lshl_add_u64 v[2:3], s[42:43], 0, v[2:3]
	v_ashrrev_i32_e32 v135, 31, v134
	v_mov_b32_e32 v0, v174
	v_lshl_add_u64 v[136:137], v[134:135], 1, v[2:3]
	s_ashr_i32 s21, s20, 31
	v_bfe_u32 v3, v0, 1, 3
	s_waitcnt vmcnt(5)
	v_lshrrev_b32_e32 v4, 4, v0
	v_bfe_u32 v5, v0, 4, 2
	v_lshlrev_b32_e32 v6, 7, v0
	v_and_b32_e32 v7, 0x780, v6
	v_bitop3_b32 v4, v4, v3, 3 bitop3:0x6c
	v_bitop3_b32 v3, v5, v3, 4 bitop3:0x36
	v_lshl_or_b32 v179, v3, 4, v7
	v_lshlrev_b32_e32 v3, 6, v0
	v_and_b32_e32 v8, 0xffffe000, v3
	v_lshlrev_b32_e32 v3, 4, v0
	s_lshl_b64 s[20:21], s[20:21], 18
	v_lshlrev_b32_e32 v2, 8, v0
	v_add_u32_e32 v180, 0, v3
	s_add_u32 s20, s40, s20
	v_and_b32_e32 v2, 0xfffff800, v2
	v_xor_b32_e32 v0, v3, v0
	v_readfirstlane_b32 s48, v180
	v_add_u32_e32 v181, 0x1000, v180
	s_addc_u32 s21, s41, s21
	v_and_or_b32 v0, v0, s45, v2
	s_mov_b32 m0, s48
	v_readfirstlane_b32 s48, v181
	v_add_u32_e32 v182, 0x2000, v180
	global_load_lds_dwordx4 v0, s[20:21]
	v_add_u32_e32 v2, 0x10000, v0
	s_mov_b32 m0, s48
	v_readfirstlane_b32 s48, v182
	v_add_u32_e32 v183, 0x3000, v180
	s_ashr_i32 s25, s24, 31
	v_lshl_or_b32 v178, v4, 4, v7
	global_load_lds_dwordx4 v2, s[20:21]
	v_add_u32_e32 v4, 0x20000, v0
	s_mov_b32 m0, s48
	v_readfirstlane_b32 s48, v183
	s_lshl_b64 s[24:25], s[24:25], 11
	v_and_b32_e32 v9, 0x2000, v6
	global_load_lds_dwordx4 v4, s[20:21]
	v_add_u32_e32 v6, 0x30000, v0
	s_mov_b32 m0, s48
	v_add_u32_e32 v184, 0x4000, v180
	s_add_u32 s46, s34, s24
	global_load_lds_dwordx4 v6, s[20:21]
	v_readfirstlane_b32 s20, v184
	v_add_u32_e32 v185, 0x5000, v180
	s_addc_u32 s47, s35, s25
	s_mov_b32 m0, s20
	v_readfirstlane_b32 s20, v185
	v_add_u32_e32 v186, 0x6000, v180
	global_load_lds_dwordx4 v0, s[46:47]
	s_mov_b32 m0, s20
	v_readfirstlane_b32 s20, v186
	v_add_u32_e32 v187, 0x7000, v180
	global_load_lds_dwordx4 v2, s[46:47]
	s_mov_b32 m0, s20
	v_readfirstlane_b32 s20, v187
	global_load_lds_dwordx4 v4, s[46:47]
	s_mov_b32 m0, s20
	s_mulk_i32 s0, 0x88
	global_load_lds_dwordx4 v6, s[46:47]
	s_sub_i32 s20, s99, s0
	s_ashr_i32 s21, s20, 31
	s_lshl_b64 s[20:21], s[20:21], 18
	s_add_u32 s20, s40, s20
	v_mov_b32_e32 v3, v1
	v_mov_b32_e32 v5, v1
	v_mov_b32_e32 v7, v1
	s_addc_u32 s21, s41, s21
	v_lshl_add_u64 v[144:145], s[20:21], 0, v[0:1]
	v_lshl_add_u64 v[146:147], s[20:21], 0, v[2:3]
	v_lshl_add_u64 v[148:149], s[20:21], 0, v[4:5]
	v_lshl_add_u64 v[150:151], s[20:21], 0, v[6:7]
	s_add_u32 s20, s36, s24
	s_addc_u32 s21, s37, s25
	v_lshl_add_u64 v[154:155], s[20:21], 0, v[2:3]
	v_mov_b32_e32 v2, v1
	v_add_u32_e32 v188, 0, v8
	v_add_u32_e32 v189, 0, v9
	v_lshl_add_u64 v[152:153], s[20:21], 0, v[0:1]
	v_lshl_add_u64 v[156:157], s[20:21], 0, v[4:5]
	v_lshl_add_u64 v[158:159], s[20:21], 0, v[6:7]
	v_mov_b32_e32 v0, v1
	v_mov_b64_e32 v[6:7], v[2:3]
	v_mov_b64_e32 v[10:11], v[2:3]
	v_mov_b64_e32 v[14:15], v[2:3]
	v_mov_b64_e32 v[18:19], v[2:3]
	v_mov_b64_e32 v[22:23], v[2:3]
	v_mov_b64_e32 v[26:27], v[2:3]
	v_mov_b64_e32 v[30:31], v[2:3]
	v_mov_b64_e32 v[34:35], v[2:3]
	v_mov_b64_e32 v[38:39], v[2:3]
	v_mov_b64_e32 v[42:43], v[2:3]
	v_mov_b64_e32 v[46:47], v[2:3]
	v_mov_b64_e32 v[50:51], v[2:3]
	s_waitcnt vmcnt(0)
	v_mov_b64_e32 v[54:55], v[2:3]
	v_mov_b64_e32 v[58:59], v[2:3]
	v_mov_b64_e32 v[62:63], v[2:3]
	v_mov_b64_e32 v[66:67], v[2:3]
	v_lshl_add_u64 v[138:139], v[136:137], 0, s[4:5]
	v_lshl_add_u64 v[140:141], v[136:137], 0, s[6:7]
	v_lshl_add_u64 v[142:143], v[136:137], 0, s[8:9]
	s_mov_b64 s[20:21], 0
	s_mov_b32 s46, s1
	v_mov_b64_e32 v[4:5], v[0:1]
	v_mov_b64_e32 v[8:9], v[0:1]
	v_mov_b64_e32 v[12:13], v[0:1]
	v_mov_b64_e32 v[16:17], v[0:1]
	v_mov_b64_e32 v[20:21], v[0:1]
	v_mov_b64_e32 v[24:25], v[0:1]
	v_mov_b64_e32 v[28:29], v[0:1]
	v_mov_b64_e32 v[32:33], v[0:1]
	v_mov_b64_e32 v[36:37], v[0:1]
	v_mov_b64_e32 v[40:41], v[0:1]
	v_mov_b64_e32 v[44:45], v[0:1]
	v_mov_b64_e32 v[48:49], v[0:1]
	v_mov_b64_e32 v[52:53], v[0:1]
	v_mov_b64_e32 v[56:57], v[0:1]
	v_mov_b64_e32 v[60:61], v[0:1]
	v_mov_b64_e32 v[64:65], v[0:1]
	s_mov_b32 s47, s1
	v_mov_b32_e32 v68, 0
	v_mov_b32_e32 v69, v1
	v_mov_b32_e32 v70, v1
	v_mov_b32_e32 v71, v1
	v_mov_b32_e32 v72, 0
	v_mov_b32_e32 v73, v1
	v_mov_b32_e32 v74, v1
	v_mov_b32_e32 v75, v1
	v_mov_b32_e32 v76, 0
	v_mov_b32_e32 v77, v1
	v_mov_b32_e32 v78, v1
	v_mov_b32_e32 v79, v1
	v_mov_b32_e32 v80, 0
	v_mov_b32_e32 v81, v1
	v_mov_b32_e32 v82, v1
	v_mov_b32_e32 v83, v1
	v_mov_b32_e32 v84, 0
	v_mov_b32_e32 v85, v1
	v_mov_b32_e32 v86, v1
	v_mov_b32_e32 v87, v1
	v_mov_b32_e32 v88, 0
	v_mov_b32_e32 v89, v1
	v_mov_b32_e32 v90, v1
	v_mov_b32_e32 v91, v1
	v_mov_b32_e32 v92, 0
	v_mov_b32_e32 v93, v1
	v_mov_b32_e32 v94, v1
	v_mov_b32_e32 v95, v1
	v_mov_b32_e32 v96, 0
	v_mov_b32_e32 v97, v1
	v_mov_b32_e32 v98, v1
	v_mov_b32_e32 v99, v1
	v_mov_b32_e32 v100, 0
	v_mov_b32_e32 v101, v1
	v_mov_b32_e32 v102, v1
	v_mov_b32_e32 v103, v1
	v_mov_b32_e32 v104, 0
	v_mov_b32_e32 v105, v1
	v_mov_b32_e32 v106, v1
	v_mov_b32_e32 v107, v1
	v_mov_b32_e32 v108, 0
	v_mov_b32_e32 v109, v1
	v_mov_b32_e32 v110, v1
	v_mov_b32_e32 v111, v1
	v_mov_b32_e32 v112, 0
	v_mov_b32_e32 v113, v1
	v_mov_b32_e32 v114, v1
	v_mov_b32_e32 v115, v1
	v_mov_b32_e32 v116, 0
	v_mov_b32_e32 v117, v1
	v_mov_b32_e32 v118, v1
	v_mov_b32_e32 v119, v1
	v_mov_b32_e32 v120, 0
	v_mov_b32_e32 v121, v1
	v_mov_b32_e32 v122, v1
	v_mov_b32_e32 v123, v1
	v_mov_b32_e32 v124, 0
	v_mov_b32_e32 v125, v1
	v_mov_b32_e32 v126, v1
	v_mov_b32_e32 v127, v1
	v_mov_b32_e32 v128, 0
	v_mov_b32_e32 v129, v1
	v_mov_b32_e32 v130, v1
	v_mov_b32_e32 v131, v1
	s_branch .LBB0_1664

.Lto_j_b4:
	s_mul_i32 s98, s98, 17
	s_add_u32 s98, s98, s99
	s_lshl_b32 s99, s98, 3
	s_or_b32 s99, s99, s20
	s_mul_hi_i32 s10, s98, 0x78787879
	s_lshr_b32 s11, s10, 31
	s_ashr_i32 s10, s10, 3
	s_add_i32 s10, s10, s11
	s_mul_i32 s11, s10, 0xffffffef
	s_add_i32 s11, s11, s98
	s_lshl_b32 s11, s11, 3
	v_mov_b32_e32 v0, v174
	s_or_b32 s12, s11, s20
	s_ashr_i32 s13, s12, 31
	v_bfe_u32 v2, v0, 1, 3
	v_lshrrev_b32_e32 v3, 4, v0
	s_waitcnt vmcnt(5)
	v_bfe_u32 v4, v0, 4, 2
	v_lshlrev_b32_e32 v5, 7, v0
	v_and_b32_e32 v6, 0x780, v5
	v_bitop3_b32 v3, v3, v2, 3 bitop3:0x6c
	v_bitop3_b32 v2, v4, v2, 4 bitop3:0x36
	s_lshl_b64 s[16:17], s[12:13], 18
	v_lshl_or_b32 v7, v3, 4, v6
	v_lshl_or_b32 v6, v2, 4, v6
	v_lshlrev_b32_e32 v2, 6, v0
	s_add_u32 s16, s38, s16
	v_and_b32_e32 v8, 0xffffe000, v2
	v_lshlrev_b32_e32 v2, 4, v0
	s_addc_u32 s17, s39, s17
	s_ashr_i32 s11, s10, 31
	v_lshlrev_b32_e32 v1, 8, v0
	v_add_u32_e32 v100, 0, v2
	s_lshl_b64 s[18:19], s[10:11], 18
	v_and_b32_e32 v1, 0xfffff800, v1
	v_xor_b32_e32 v0, v2, v0
	v_readfirstlane_b32 s11, v100
	v_add_u32_e32 v101, 0x1000, v100
	v_and_or_b32 v64, v0, s25, v1
	s_mov_b32 m0, s11
	v_readfirstlane_b32 s11, v101
	v_add_u32_e32 v102, 0x2000, v100
	global_load_lds_dwordx4 v64, s[16:17]
	v_add_u32_e32 v0, 0x10000, v64
	s_mov_b32 m0, s11
	v_readfirstlane_b32 s11, v102
	v_add_u32_e32 v103, 0x3000, v100
	global_load_lds_dwordx4 v0, s[16:17]
	v_add_u32_e32 v2, 0x20000, v64
	s_mov_b32 m0, s11
	v_readfirstlane_b32 s11, v103
	v_add_u32_e32 v104, 0x4000, v100
	s_add_u32 s26, s70, s18
	global_load_lds_dwordx4 v2, s[16:17]
	v_add_u32_e32 v4, 0x30000, v64
	s_mov_b32 m0, s11
	v_readfirstlane_b32 s11, v104
	v_add_u32_e32 v105, 0x5000, v100
	s_addc_u32 s27, s71, s19
	global_load_lds_dwordx4 v4, s[16:17]
	s_mov_b32 m0, s11
	v_readfirstlane_b32 s11, v105
	v_add_u32_e32 v106, 0x6000, v100
	global_load_lds_dwordx4 v64, s[26:27]
	s_mov_b32 m0, s11
	v_readfirstlane_b32 s11, v106
	v_add_u32_e32 v107, 0x7000, v100
	global_load_lds_dwordx4 v0, s[26:27]
	s_mov_b32 m0, s11
	v_readfirstlane_b32 s11, v107
	global_load_lds_dwordx4 v2, s[26:27]
	s_mov_b32 m0, s11
	s_mul_i32 s11, s10, 0x88
	global_load_lds_dwordx4 v4, s[26:27]
	s_sub_i32 s16, s99, s11
	s_ashr_i32 s17, s16, 31
	s_lshl_b64 s[16:17], s[16:17], 18
	s_add_u32 s16, s38, s16
	v_and_b32_e32 v9, 0x2000, v5
	v_mov_b32_e32 v1, v65
	v_mov_b32_e32 v3, v65
	v_mov_b32_e32 v5, v65
	s_addc_u32 s17, s39, s17
	v_lshl_add_u64 v[66:67], s[16:17], 0, v[64:65]
	v_lshl_add_u64 v[68:69], s[16:17], 0, v[0:1]
	v_lshl_add_u64 v[70:71], s[16:17], 0, v[2:3]
	v_lshl_add_u64 v[72:73], s[16:17], 0, v[4:5]
	s_add_u32 s16, s36, s18
	v_add_u32_e32 v8, 0, v8
	v_add_u32_e32 v9, 0, v9
	s_addc_u32 s17, s37, s19
	v_lshl_add_u64 v[74:75], s[16:17], 0, v[64:65]
	v_lshl_add_u64 v[76:77], s[16:17], 0, v[0:1]
	v_lshl_add_u64 v[78:79], s[16:17], 0, v[2:3]
	v_lshl_add_u64 v[80:81], s[16:17], 0, v[4:5]
	s_mov_b64 s[16:17], 0
	v_add_u32_e32 v64, 0x8000, v100
	v_add_u32_e32 v108, 0x9000, v100
	v_add_u32_e32 v109, 0xa000, v100
	v_add_u32_e32 v110, 0xb000, v100
	v_add_u32_e32 v111, 0xc000, v100
	v_add_u32_e32 v112, 0xd000, v100
	v_add_u32_e32 v113, 0xe000, v100
	v_add_u32_e32 v114, 0xf000, v100
	v_add_u32_e32 v115, v8, v7
	v_add_u32_e32 v116, v9, v7
	v_add_u32_e32 v117, v8, v6
	v_add_u32_e32 v118, v9, v6
	s_mov_b32 s11, 0
	v_mov_b32_e32 v0, 0
	v_mov_b32_e32 v2, v65
	v_mov_b32_e32 v4, 0
	v_mov_b32_e32 v6, v65
	v_mov_b32_e32 v7, v65
	v_mov_b32_e32 v8, 0
	v_mov_b32_e32 v9, v65
	v_mov_b32_e32 v10, v65
	v_mov_b32_e32 v11, v65
	v_mov_b32_e32 v12, 0
	v_mov_b32_e32 v13, v65
	v_mov_b32_e32 v14, v65
	v_mov_b32_e32 v15, v65
	v_mov_b32_e32 v16, 0
	v_mov_b32_e32 v17, v65
	v_mov_b32_e32 v18, v65
	v_mov_b32_e32 v19, v65
	v_mov_b32_e32 v20, 0
	v_mov_b32_e32 v21, v65
	v_mov_b32_e32 v22, v65
	v_mov_b32_e32 v23, v65
	v_mov_b32_e32 v24, 0
	v_mov_b32_e32 v25, v65
	v_mov_b32_e32 v26, v65
	v_mov_b32_e32 v27, v65
	v_mov_b32_e32 v28, 0
	v_mov_b32_e32 v29, v65
	v_mov_b32_e32 v30, v65
	v_mov_b32_e32 v31, v65
	v_mov_b32_e32 v32, 0
	v_mov_b32_e32 v33, v65
	v_mov_b32_e32 v34, v65
	v_mov_b32_e32 v35, v65
	v_mov_b32_e32 v36, 0
	v_mov_b32_e32 v37, v65
	v_mov_b32_e32 v38, v65
	v_mov_b32_e32 v39, v65
	v_mov_b32_e32 v40, 0
	v_mov_b32_e32 v41, v65
	v_mov_b32_e32 v42, v65
	v_mov_b32_e32 v43, v65
	v_mov_b32_e32 v44, 0
	v_mov_b32_e32 v45, v65
	v_mov_b32_e32 v46, v65
	v_mov_b32_e32 v47, v65
	v_mov_b32_e32 v48, 0
	v_mov_b32_e32 v49, v65
	v_mov_b32_e32 v50, v65
	v_mov_b32_e32 v51, v65
	v_mov_b32_e32 v52, 0
	v_mov_b32_e32 v53, v65
	s_waitcnt vmcnt(0)
	v_mov_b32_e32 v54, v65
	v_mov_b32_e32 v55, v65
	v_mov_b32_e32 v56, 0
	v_mov_b32_e32 v57, v65
	v_mov_b32_e32 v58, v65
	v_mov_b32_e32 v59, v65
	v_mov_b32_e32 v60, 0
	v_mov_b32_e32 v61, v65
	v_mov_b32_e32 v62, v65
	v_mov_b32_e32 v63, v65
	s_branch .LBB0_1735

.LBB0_1934:
	s_cmp_ge_u32 s12, 64
	s_cbranch_scc1 .Lto_g1_b5
	s_sub_u32 s99, s12, 0
	s_lshr_b32 s98, s99, 3
	s_and_b32 s99, s99, 7
	s_branch .Lto_j_b5
.Lto_g1_b5:
	s_sub_u32 s99, s12, 64
	s_mul_hi_u32 s98, s99, 0x38e38e39
	s_lshr_b32 s98, s98, 1
	s_mul_i32 s100, s98, 9
	s_sub_u32 s99, s99, s100
	s_add_u32 s99, s99, 8
.Lto_j_b5:
	s_mul_i32 s98, s98, 17
	s_add_u32 s98, s98, s99
	s_lshl_b32 s99, s98, 3
	s_or_b32 s99, s99, s13
	s_mul_hi_i32 s8, s98, 0x78787879
	s_lshr_b32 s9, s8, 31
	s_ashr_i32 s20, s8, 3
	s_add_i32 s20, s20, s9
	v_mov_b32_e32 v0, v174
	s_mul_i32 s8, s20, 0xffffffef
	s_add_i32 s8, s8, s98
	v_bfe_u32 v2, v0, 1, 3
	v_lshrrev_b32_e32 v3, 4, v0
	s_waitcnt vmcnt(5)
	v_bfe_u32 v4, v0, 4, 2
	v_lshlrev_b32_e32 v5, 7, v0
	v_and_b32_e32 v6, 0x780, v5
	v_bitop3_b32 v3, v3, v2, 3 bitop3:0x6c
	v_bitop3_b32 v2, v4, v2, 4 bitop3:0x36
	s_lshl_b32 s8, s8, 3
	v_lshl_or_b32 v7, v3, 4, v6
	v_lshl_or_b32 v6, v2, 4, v6
	v_lshlrev_b32_e32 v2, 6, v0
	s_or_b32 s21, s8, s13
	v_and_b32_e32 v8, 0xffffe000, v2
	v_lshlrev_b32_e32 v2, 4, v0
	s_mul_i32 s8, s21, 0xb0000
	v_lshrrev_b32_e32 v1, 3, v0
	v_add_u32_e32 v100, 0, v2
	s_mul_hi_i32 s9, s21, 0xb0000
	s_add_u32 s8, s42, s8
	v_mul_lo_u32 v1, v1, s18
	v_xor_b32_e32 v0, v2, v0
	v_readfirstlane_b32 s24, v100
	v_add_u32_e32 v101, 0x1000, v100
	s_addc_u32 s9, s43, s9
	v_and_or_b32 v64, v0, s19, v1
	s_mov_b32 m0, s24
	v_readfirstlane_b32 s24, v101
	v_add_u32_e32 v102, 0x2000, v100
	global_load_lds_dwordx4 v64, s[8:9]
	v_add_u32_e32 v0, 0x2c000, v64
	s_mov_b32 m0, s24
	v_readfirstlane_b32 s24, v102
	v_add_u32_e32 v103, 0x3000, v100
	global_load_lds_dwordx4 v0, s[8:9]
	v_add_u32_e32 v2, 0x58000, v64
	s_mov_b32 m0, s24
	v_readfirstlane_b32 s24, v103
	s_mul_i32 s23, s20, 0xb0000
	global_load_lds_dwordx4 v2, s[8:9]
	v_add_u32_e32 v4, 0x84000, v64
	s_mov_b32 m0, s24
	v_add_u32_e32 v104, 0x4000, v100
	s_mul_hi_i32 s22, s20, 0xb0000
	s_add_u32 s10, s88, s23
	global_load_lds_dwordx4 v4, s[8:9]
	v_readfirstlane_b32 s8, v104
	v_add_u32_e32 v105, 0x5000, v100
	s_addc_u32 s11, s89, s22
	s_mov_b32 m0, s8
	v_readfirstlane_b32 s8, v105
	v_add_u32_e32 v106, 0x6000, v100
	global_load_lds_dwordx4 v64, s[10:11]
	s_mov_b32 m0, s8
	v_readfirstlane_b32 s8, v106
	v_add_u32_e32 v107, 0x7000, v100
	global_load_lds_dwordx4 v0, s[10:11]
	s_mov_b32 m0, s8
	v_readfirstlane_b32 s8, v107
	global_load_lds_dwordx4 v2, s[10:11]
	s_mov_b32 m0, s8
	s_mul_i32 s8, s20, 0x88
	global_load_lds_dwordx4 v4, s[10:11]
	s_sub_i32 s8, s99, s8
	s_mul_hi_i32 s9, s8, 0xb0000
	s_mul_i32 s8, s8, 0xb0000
	s_add_u32 s8, s42, s8
	v_and_b32_e32 v9, 0x2000, v5
	v_mov_b32_e32 v1, v65
	v_mov_b32_e32 v3, v65
	v_mov_b32_e32 v5, v65
	s_addc_u32 s9, s43, s9
	v_lshl_add_u64 v[66:67], s[8:9], 0, v[64:65]
	v_lshl_add_u64 v[68:69], s[8:9], 0, v[0:1]
	v_lshl_add_u64 v[70:71], s[8:9], 0, v[2:3]
	v_lshl_add_u64 v[72:73], s[8:9], 0, v[4:5]
	s_add_u32 s8, s36, s23
	v_add_u32_e32 v8, 0, v8
	v_add_u32_e32 v9, 0, v9
	s_addc_u32 s9, s37, s22
	v_lshl_add_u64 v[74:75], s[8:9], 0, v[64:65]
	v_lshl_add_u64 v[76:77], s[8:9], 0, v[0:1]
	v_lshl_add_u64 v[78:79], s[8:9], 0, v[2:3]
	v_lshl_add_u64 v[80:81], s[8:9], 0, v[4:5]
	s_mov_b64 s[8:9], 0
	v_add_u32_e32 v64, 0x8000, v100
	v_add_u32_e32 v108, 0x9000, v100
	v_add_u32_e32 v109, 0xa000, v100
	v_add_u32_e32 v110, 0xb000, v100
	v_add_u32_e32 v111, 0xc000, v100
	v_add_u32_e32 v112, 0xd000, v100
	v_add_u32_e32 v113, 0xe000, v100
	v_add_u32_e32 v114, 0xf000, v100
	v_add_u32_e32 v115, v8, v7
	v_add_u32_e32 v116, v9, v7
	v_add_u32_e32 v117, v8, v6
	v_add_u32_e32 v118, v9, v6
	s_mov_b32 s22, 0
	v_mov_b32_e32 v0, 0
	v_mov_b32_e32 v2, v65
	v_mov_b32_e32 v4, 0
	v_mov_b32_e32 v6, v65
	v_mov_b32_e32 v7, v65
	v_mov_b32_e32 v8, 0
	v_mov_b32_e32 v9, v65
	v_mov_b32_e32 v10, v65
	v_mov_b32_e32 v11, v65
	v_mov_b32_e32 v12, 0
	v_mov_b32_e32 v13, v65
	v_mov_b32_e32 v14, v65
	v_mov_b32_e32 v15, v65
	v_mov_b32_e32 v16, 0
	v_mov_b32_e32 v17, v65
	v_mov_b32_e32 v18, v65
	v_mov_b32_e32 v19, v65
	v_mov_b32_e32 v20, 0
	v_mov_b32_e32 v21, v65
	v_mov_b32_e32 v22, v65
	v_mov_b32_e32 v23, v65
	v_mov_b32_e32 v24, 0
	v_mov_b32_e32 v25, v65
	v_mov_b32_e32 v26, v65
	v_mov_b32_e32 v27, v65
	v_mov_b32_e32 v28, 0
	v_mov_b32_e32 v29, v65
	v_mov_b32_e32 v30, v65
	v_mov_b32_e32 v31, v65
	v_mov_b32_e32 v32, 0
	v_mov_b32_e32 v33, v65
	v_mov_b32_e32 v34, v65
	v_mov_b32_e32 v35, v65
	v_mov_b32_e32 v36, 0
	v_mov_b32_e32 v37, v65
	v_mov_b32_e32 v38, v65
	v_mov_b32_e32 v39, v65
	v_mov_b32_e32 v40, 0
	v_mov_b32_e32 v41, v65
	v_mov_b32_e32 v42, v65
	v_mov_b32_e32 v43, v65
	v_mov_b32_e32 v44, 0
	v_mov_b32_e32 v45, v65
	v_mov_b32_e32 v46, v65
	v_mov_b32_e32 v47, v65
	v_mov_b32_e32 v48, 0
	v_mov_b32_e32 v49, v65
	v_mov_b32_e32 v50, v65
	v_mov_b32_e32 v51, v65
	v_mov_b32_e32 v52, 0
	v_mov_b32_e32 v53, v65
	s_waitcnt vmcnt(0)
	v_mov_b32_e32 v54, v65
	v_mov_b32_e32 v55, v65
	v_mov_b32_e32 v56, 0
	v_mov_b32_e32 v57, v65
	v_mov_b32_e32 v58, v65
	v_mov_b32_e32 v59, v65
	v_mov_b32_e32 v60, 0
	v_mov_b32_e32 v61, v65
	v_mov_b32_e32 v62, v65
	v_mov_b32_e32 v63, v65
	s_branch .LBB0_1936
